# hg_prep_chunk: wait for the last gate load taken before the conditional 2-byte stores instead of a full drain after them
# speedup vs baseline: 1.0114x; 1.0026x over previous
; #define LAS __attribute__((address_space(3)))
; __device__ __forceinline__ float bf1(bf16_t b) { return __uint_as_float(((unsigned)b) << 16); }
; __device__ __forceinline__ bf16_t f2bf(float f) { return (bf16_t)(cvt_pk_bf16(f, 0.f) & 0xffffu); }
; __device__ __forceinline__ float sigmoidf_(float x) { return __builtin_amdgcn_rcpf(1.0f + __expf(-x)); }
; __device__ __forceinline__ void hg_prep_chunk(const Params& p, LAS unsigned char* lds, int task) {
;     ...
;     const float l0 = p.in[8][h * 128 + c], l1 = p.in[8][512 + h * 128 + c]; const float lb = 1.0f / (1.0f + __expf(l1 - l0)), omlb = 1.0f - lb;
;     const bool valid = sg * 16 < TC;
;     float cp[16], kx[16], qv[16], vv[16]; float run = 1.f;
;     {
;         const bf16_t* rp = phg + (size_t)(row0 + (valid ? sg * 16 : 0)) * HGC + h * 128 + c; bf16_t rq[16], rf[16], rv[16];
; #pragma unroll
;         for (int j = 0; j < 16; ++j) { rq[j] = rp[(size_t)j * HGC]; rf[j] = rp[(size_t)j * HGC + 512]; rv[j] = rp[(size_t)j * HGC + 1024]; }
; #pragma unroll
;         for (int j = 0; j < 16; ++j) {
;             const float sgm = sigmoidf_(bf1(rf[j])); const float f = valid ? lb + omlb * sgm : 1.0f; run *= f; cp[j] = run;
;             kx[j] = valid ? omlb * (1.0f - sgm) : 0.f; qv[j] = valid ? bf1(rq[j]) : 0.f; vv[j] = valid ? bf1(rv[j]) : 0.f;
;         }
;     }
;     *(LAS float*)(lds + SEG + (sg * 128 + c) * 4) = run;
;     __syncthreads();
;     float pre = 1.f, tot = 1.f;
; #pragma unroll
;     for (int s2 = 0; s2 < 4; ++s2) { const float x = *(const LAS float*)(lds + SEG + (s2 * 128 + c) * 4); tot *= x; if (s2 < sg) pre *= x; }
;     {
;         float kd[16];
; #pragma unroll
;         for (int j = 0; j < 16; ++j) {
;             const float P = pre * cp[j]; const int t = sg * 16 + j; const float qg = qv[j] * P, kg = kx[j] * __builtin_amdgcn_rcpf(P);
;             const bf16_t qgb = f2bf(qg);
;             *(LAS bf16_t*)(lds + QG + t * 272 + c * 2) = qgb;
;             *(LAS bf16_t*)(lds + KG + t * 272 + c * 2) = f2bf(kg);
;             kd[j] = kg * tot;
;             if (valid) phg[(size_t)(row0 + t) * HGC + h * 128 + c] = qgb;
.LBB0_370:
	s_or_b64 exec, exec, s[10:11]
	s_waitcnt vmcnt(46)
	v_sub_f32_e32 v0, v51, v33
	v_mul_f32_e32 v0, 0x3fb8aa3b, v0
	v_exp_f32_e32 v0, v0
	s_waitcnt vmcnt(45)
	v_lshlrev_b32_e32 v1, 16, v52
	v_mul_f32_e32 v1, 0xbfb8aa3b, v1
	v_exp_f32_e32 v1, v1
	v_add_f32_e32 v0, 1.0, v0
	v_div_scale_f32 v33, s[10:11], v0, v0, 1.0
	v_rcp_f32_e32 v51, v33
	v_div_scale_f32 v52, vcc, 1.0, v0, 1.0
	v_add_f32_e32 v1, 1.0, v1
	v_fma_f32 v57, -v33, v51, 1.0
	v_fmac_f32_e32 v51, v57, v51
	v_mul_f32_e32 v57, v52, v51
	v_fma_f32 v58, -v33, v57, v52
	v_fmac_f32_e32 v57, v58, v51
	v_fma_f32 v33, -v33, v57, v52
	v_div_fmas_f32 v33, v33, v51, v57
	v_div_fixup_f32 v0, v33, v0, 1.0
	s_waitcnt vmcnt(36)
	v_lshlrev_b32_e32 v33, 16, v55
	v_mul_f32_e32 v33, 0xbfb8aa3b, v33
	v_exp_f32_e32 v51, v33
	v_rcp_f32_e32 v1, v1
	v_sub_f32_e32 v33, 1.0, v0
	s_waitcnt vmcnt(34)
	v_lshlrev_b32_e32 v52, 16, v54
	v_add_f32_e32 v51, 1.0, v51
	v_rcp_f32_e32 v75, v51
	v_fma_f32 v51, v33, v1, v0
	v_cndmask_b32_e64 v77, 1.0, v51, s[4:5]
	s_waitcnt vmcnt(5)
	v_lshlrev_b32_e32 v51, 16, v56
	v_mul_f32_e32 v51, 0xbfb8aa3b, v51
	v_exp_f32_e32 v51, v51
	v_mul_f32_e32 v52, 0xbfb8aa3b, v52
	v_exp_f32_e32 v52, v52
	v_sub_f32_e32 v78, 1.0, v1
	v_fma_f32 v1, v33, v75, v0
	v_add_f32_e32 v51, 1.0, v51
	v_cndmask_b32_e64 v1, 1.0, v1, s[4:5]
	v_rcp_f32_e32 v73, v51
	v_lshlrev_b32_e32 v47, 16, v47
	v_mul_f32_e32 v76, v77, v1
	v_add_f32_e32 v1, 1.0, v52
	v_mul_f32_e32 v47, 0xbfb8aa3b, v47
	v_rcp_f32_e32 v70, v1
	v_exp_f32_e32 v47, v47
	v_lshlrev_b32_e32 v50, 16, v50
	v_mul_f32_e32 v50, 0xbfb8aa3b, v50
	v_fma_f32 v1, v33, v73, v0
	v_exp_f32_e32 v50, v50
	v_cndmask_b32_e64 v1, 1.0, v1, s[4:5]
	v_mul_f32_e32 v74, v76, v1
	v_fma_f32 v1, v33, v70, v0
	v_add_f32_e32 v47, 1.0, v47
	v_cndmask_b32_e64 v1, 1.0, v1, s[4:5]
	v_rcp_f32_e32 v68, v47
	v_lshlrev_b32_e32 v42, 16, v42
	v_mul_f32_e32 v72, v74, v1
	v_add_f32_e32 v1, 1.0, v50
	v_mul_f32_e32 v42, 0xbfb8aa3b, v42
	v_rcp_f32_e32 v66, v1
	v_exp_f32_e32 v42, v42
	v_lshlrev_b32_e32 v43, 16, v43
	v_mul_f32_e32 v43, 0xbfb8aa3b, v43
	v_fma_f32 v1, v33, v68, v0
	v_exp_f32_e32 v43, v43
	v_cndmask_b32_e64 v1, 1.0, v1, s[4:5]
	v_mul_f32_e32 v69, v72, v1
	v_fma_f32 v1, v33, v66, v0
	v_add_f32_e32 v42, 1.0, v42
	v_cndmask_b32_e64 v1, 1.0, v1, s[4:5]
	v_rcp_f32_e32 v64, v42
	v_lshlrev_b32_e32 v42, 16, v46
	v_mul_f32_e32 v67, v69, v1
	v_add_f32_e32 v1, 1.0, v43
	v_mul_f32_e32 v42, 0xbfb8aa3b, v42
	v_rcp_f32_e32 v62, v1
	v_exp_f32_e32 v42, v42
	v_lshlrev_b32_e32 v43, 16, v53
	v_mul_f32_e32 v43, 0xbfb8aa3b, v43
	v_fma_f32 v1, v33, v64, v0
	v_exp_f32_e32 v43, v43
	v_cndmask_b32_e64 v1, 1.0, v1, s[4:5]
	v_mul_f32_e32 v65, v67, v1
	v_fma_f32 v1, v33, v62, v0
	v_add_f32_e32 v42, 1.0, v42
	v_cndmask_b32_e64 v1, 1.0, v1, s[4:5]
	v_rcp_f32_e32 v60, v42
	v_lshlrev_b32_e32 v3, 16, v3
	v_mul_f32_e32 v63, v65, v1
	v_add_f32_e32 v1, 1.0, v43
	v_mul_f32_e32 v3, 0xbfb8aa3b, v3
	v_rcp_f32_e32 v58, v1
	v_exp_f32_e32 v3, v3
	v_lshlrev_b32_e32 v42, 16, v48
	v_mul_f32_e32 v42, 0xbfb8aa3b, v42
	v_fma_f32 v1, v33, v60, v0
	v_exp_f32_e32 v42, v42
	v_cndmask_b32_e64 v1, 1.0, v1, s[4:5]
	v_mul_f32_e32 v61, v63, v1
	v_fma_f32 v1, v33, v58, v0
	v_add_f32_e32 v3, 1.0, v3
	v_cndmask_b32_e64 v1, 1.0, v1, s[4:5]
	v_rcp_f32_e32 v56, v3
	v_lshlrev_b32_e32 v2, 16, v2
	v_mul_f32_e32 v59, v61, v1
	v_add_f32_e32 v1, 1.0, v42
	v_mul_f32_e32 v2, 0xbfb8aa3b, v2
	v_rcp_f32_e32 v54, v1
	v_exp_f32_e32 v2, v2
	v_lshlrev_b32_e32 v3, 16, v6
	v_mul_f32_e32 v3, 0xbfb8aa3b, v3
	v_fma_f32 v1, v33, v56, v0
	v_exp_f32_e32 v3, v3
	v_cndmask_b32_e64 v1, 1.0, v1, s[4:5]
	v_mul_f32_e32 v57, v59, v1
	v_fma_f32 v1, v33, v54, v0
	v_add_f32_e32 v2, 1.0, v2
	v_cndmask_b32_e64 v1, 1.0, v1, s[4:5]
	v_rcp_f32_e32 v52, v2
	v_mul_f32_e32 v55, v57, v1
	v_add_f32_e32 v1, 1.0, v3
	s_waitcnt vmcnt(4)
	v_lshlrev_b32_e32 v2, 16, v5
	v_rcp_f32_e32 v50, v1
	v_mul_f32_e32 v2, 0xbfb8aa3b, v2
	s_waitcnt vmcnt(0)
	v_lshlrev_b32_e32 v3, 16, v4
	v_exp_f32_e32 v2, v2
	v_mul_f32_e32 v3, 0xbfb8aa3b, v3
	v_fma_f32 v1, v33, v52, v0
	v_exp_f32_e32 v3, v3
	v_cndmask_b32_e64 v1, 1.0, v1, s[4:5]
	v_mul_f32_e32 v53, v55, v1
	v_fma_f32 v1, v33, v50, v0
	v_cndmask_b32_e64 v1, 1.0, v1, s[4:5]
	v_add_f32_e32 v2, 1.0, v2
	v_rcp_f32_e32 v46, v2
	v_mul_f32_e32 v51, v53, v1
	v_add_f32_e32 v1, 1.0, v3
	v_rcp_f32_e32 v42, v1
	v_fma_f32 v1, v33, v46, v0
	v_cndmask_b32_e64 v1, 1.0, v1, s[4:5]
	v_mul_f32_e32 v47, v51, v1
	v_fmac_f32_e32 v0, v33, v42
	v_cndmask_b32_e64 v0, 1.0, v0, s[4:5]
	v_mul_f32_e32 v43, v47, v0
	v_lshl_add_u32 v0, v8, 2, 0
	v_lshl_add_u32 v4, v9, 2, 0
	ds_write_b32 v0, v43 offset:62464
	s_waitcnt lgkmcnt(0)
	s_barrier
	ds_read2st64_b32 v[0:1], v4 offset0:244 offset1:246
	v_mul_f32_e32 v2, v33, v78
	v_cndmask_b32_e64 v78, 0, v2, s[4:5]
	ds_read2st64_b32 v[2:3], v4 offset0:248 offset1:250
	v_cmp_lt_i32_e32 vcc, 0, v11
	s_lshl_b32 s8, s53, 1
	s_add_u32 s10, s0, s8
	s_waitcnt lgkmcnt(1)
	v_cndmask_b32_e32 v5, 1.0, v0, vcc
	v_mul_f32_e32 v6, v5, v1
	v_cmp_lt_i32_e32 vcc, 1, v11
	s_addc_u32 s11, s1, 0
	s_nop 0
	v_cndmask_b32_e32 v5, v5, v6, vcc
	s_waitcnt lgkmcnt(0)
	v_mul_f32_e32 v6, v2, v5
	v_cmp_lt_i32_e32 vcc, 2, v11
	s_nop 1
	v_cndmask_b32_e32 v5, v5, v6, vcc
	v_mul_f32_e32 v6, v3, v5
	v_cmp_lt_i32_e32 vcc, 3, v11
	s_nop 1
	v_cndmask_b32_e32 v48, v5, v6, vcc
	v_mul_f32_e32 v77, v77, v48
	v_rcp_f32_e32 v79, v77
	v_sub_u32_e32 v6, v4, v12
	v_lshl_add_u64 v[4:5], s[10:11], 0, v[12:13]
	v_mul_f32_e32 v71, v71, v77
	v_mul_f32_e32 v12, v78, v79
	v_cvt_pk_bf16_f32 v71, v71, s0
	v_mad_u64_u32 v[78:79], s[10:11], v11, s60, v[6:7]
	v_cvt_pk_bf16_f32 v77, v12, s0
	ds_write_b16 v78, v71
	ds_write_b16 v78, v77 offset:17408
	s_and_saveexec_b64 s[10:11], s[4:5]
	s_cbranch_execz .LBB0_372
	v_add_u32_e32 v78, s70, v10
	v_ashrrev_i32_e32 v79, 31, v78
	v_lshlrev_b64 v[78:79], 12, v[78:79]
	v_lshl_add_u64 v[78:79], v[4:5], 0, v[78:79]
	global_store_short v[78:79], v71, off

; #define LAS __attribute__((address_space(3)))
; __device__ __forceinline__ bf16_t f2bf(float f) { return (bf16_t)(cvt_pk_bf16(f, 0.f) & 0xffffu); }
; __device__ __forceinline__ void hg_prep_chunk(const Params& p, LAS unsigned char* lds, int task) {
;     ...
;     for (int s2 = 0; s2 < 4; ++s2) { const float x = *(const LAS float*)(lds + SEG + (s2 * 128 + c) * 4); tot *= x; if (s2 < sg) pre *= x; }
;     {
;         float kd[16];
; #pragma unroll
;         for (int j = 0; j < 16; ++j) {
;             const float P = pre * cp[j]; const int t = sg * 16 + j; const float qg = qv[j] * P, kg = kx[j] * __builtin_amdgcn_rcpf(P);
;             const bf16_t qgb = f2bf(qg);
;             *(LAS bf16_t*)(lds + QG + t * 272 + c * 2) = qgb;
;             *(LAS bf16_t*)(lds + KG + t * 272 + c * 2) = f2bf(kg);
;             kd[j] = kg * tot;
;             if (valid) phg[(size_t)(row0 + t) * HGC + h * 128 + c] = qgb;
;         }
;         const u32x4 v0 = pack8(vv), v1 = pack8(vv + 8);
;         *(LAS u32x4*)(lds + VT + c * 144 + sg * 32) = v0; *(LAS u32x4*)(lds + VT + c * 144 + sg * 32 + 16) = v1;
;         if (valid) {
;             const int lin = c * TC + sg * 16; bf16_t* dst = phg + (size_t)(row0 + (lin >> 7)) * HGC + h * 128 + (lin & 127);
;             *(u32x4*)(dst + 512) = pack8(kd); *(u32x4*)(dst + 512 + 8) = pack8(kd + 8);
;             *(u32x4*)(dst + 1024) = v0; *(u32x4*)(dst + 1024 + 8) = v1;
.LBB0_402:
	s_or_b64 exec, exec, s[10:11]
	v_mul_f32_e32 v0, v0, v1
	v_mul_f32_e32 v0, v0, v2
	v_mul_f32_e32 v29, v0, v3
	v_lshlrev_b32_e32 v1, 16, v7
	v_lshlrev_b32_e32 v2, 16, v17
	v_lshlrev_b32_e32 v3, 16, v14
	v_lshlrev_b32_e32 v4, 16, v15
	v_lshlrev_b32_e32 v7, 16, v20
	v_lshlrev_b32_e32 v14, 16, v25
	v_lshlrev_b32_e32 v0, 16, v18
	v_cndmask_b32_e64 v1, 0, v1, s[4:5]
	v_cndmask_b32_e64 v2, 0, v2, s[4:5]
	v_cndmask_b32_e64 v3, 0, v3, s[4:5]
	v_cndmask_b32_e64 v4, 0, v4, s[4:5]
	v_lshlrev_b32_e32 v5, 16, v19
	v_lshlrev_b32_e32 v6, 16, v16
	v_cndmask_b32_e64 v7, 0, v7, s[4:5]
	v_cndmask_b32_e64 v14, 0, v14, s[4:5]
	v_lshlrev_b32_e32 v15, 16, v21
	v_lshlrev_b32_e32 v16, 16, v24
	v_lshlrev_b32_e32 v17, 16, v22
	v_lshlrev_b32_e32 v18, 16, v23
	v_lshlrev_b32_e32 v19, 16, v26
	s_nop 0
	v_lshlrev_b32_e32 v20, 16, v27
	v_cndmask_b32_e64 v0, 0, v0, s[4:5]
	v_cndmask_b32_e64 v5, 0, v5, s[4:5]
	v_cndmask_b32_e64 v6, 0, v6, s[4:5]
	v_cndmask_b32_e64 v15, 0, v15, s[4:5]
	v_cndmask_b32_e64 v16, 0, v16, s[4:5]
	v_cndmask_b32_e64 v17, 0, v17, s[4:5]
	v_cndmask_b32_e64 v18, 0, v18, s[4:5]
	v_cndmask_b32_e64 v19, 0, v19, s[4:5]
	v_cndmask_b32_e64 v20, 0, v20, s[4:5]
	v_cvt_pk_bf16_f32 v1, v1, v2
	v_cvt_pk_bf16_f32 v2, v3, v4
	v_cvt_pk_bf16_f32 v4, v7, v14
	v_mul_u32_u24_e32 v14, 0x90, v9
	v_lshlrev_b32_e32 v11, 5, v11
	v_cvt_pk_bf16_f32 v0, v28, v0
	v_cvt_pk_bf16_f32 v3, v5, v6
	v_cvt_pk_bf16_f32 v5, v15, v16
	v_cvt_pk_bf16_f32 v6, v17, v18
	v_cvt_pk_bf16_f32 v7, v19, v20
	v_add3_u32 v11, 0, v14, v11
	ds_write_b128 v11, v[0:3] offset:34816
	ds_write_b128 v11, v[4:7] offset:34832
	s_and_saveexec_b64 s[10:11], s[4:5]
	s_cbranch_execz .LBB0_404
	v_mad_u32_u24 v9, s69, v9, v10
	v_ashrrev_i32_e32 v10, 7, v9
	v_add_u32_e32 v10, s70, v10
	v_ashrrev_i32_e32 v11, 31, v10
	v_lshlrev_b64 v[10:11], 12, v[10:11]
	v_lshl_add_u64 v[10:11], s[0:1], 0, v[10:11]
	v_and_b32_e32 v9, 0x70, v9
	v_mul_f32_e32 v19, v29, v30
	v_mul_f32_e32 v17, v29, v38
	v_mul_f32_e32 v26, v29, v39
	v_mul_f32_e32 v16, v29, v41
	v_mul_f32_e32 v27, v29, v44
	v_mul_f32_e32 v15, v29, v49
	v_mul_f32_e32 v28, v29, v45
	v_mul_f32_e32 v14, v29, v40
	v_mul_f32_e32 v30, v29, v12
	v_lshl_add_u64 v[10:11], v[10:11], 0, s[8:9]
	v_lshlrev_b32_e32 v12, 1, v9
	v_mul_f32_e32 v18, v29, v33
	v_mul_f32_e32 v20, v29, v31
	v_mul_f32_e32 v21, v29, v32
	v_mul_f32_e32 v22, v29, v34
	v_mul_f32_e32 v23, v29, v35
	v_mul_f32_e32 v24, v29, v36
	v_mul_f32_e32 v25, v29, v37
	v_lshl_add_u64 v[10:11], v[10:11], 0, v[12:13]
	v_cvt_pk_bf16_f32 v14, v30, v14
	v_cvt_pk_bf16_f32 v15, v28, v15
	v_cvt_pk_bf16_f32 v16, v27, v16
	v_cvt_pk_bf16_f32 v17, v26, v17
	global_store_dwordx4 v[10:11], v[14:17], off offset:1024
	s_nop 1
	v_cvt_pk_bf16_f32 v14, v25, v24
	v_cvt_pk_bf16_f32 v15, v23, v22
	v_cvt_pk_bf16_f32 v16, v21, v20
	v_cvt_pk_bf16_f32 v17, v19, v18
	global_store_dwordx4 v[10:11], v[14:17], off offset:1040
	global_store_dwordx4 v[10:11], v[0:3], off offset:2048
	global_store_dwordx4 v[10:11], v[4:7], off offset:2064
